# scan: pair halves placed four dispatch slots apart on the same XCD instead of adjacent slots
# speedup vs baseline: 1.0062x; 1.0062x over previous
.LBB0_154:
	s_and_b64 vcc, exec, s[0:1]
	s_cbranch_vccz .LBB0_168
	s_and_b32 s98, s80, 7
	s_lshl_b32 s98, s98, 3
	s_lshr_b32 s99, s80, 3
	s_and_b32 s80, s99, 3
	s_lshl_b32 s80, s80, 1
	s_lshr_b32 s99, s99, 2
	s_or_b32 s99, s80, s99
	s_or_b32 s80, s98, s99
	s_ashr_i32 s0, s80, 1
	s_ashr_i32 s1, s0, 31
	s_lshl_b64 s[4:5], s[0:1], 8
	s_add_u32 s4, s2, s4
	s_addc_u32 s5, s3, s5
	v_lshlrev_b32_e32 v0, 2, v160
	v_lshl_add_u64 v[2:3], s[4:5], 0, v[0:1]
	v_add_co_u32_e32 v2, vcc, 0x300000, v2
	v_readlane_b32 s4, v254, 48
	s_nop 0
	v_addc_co_u32_e32 v3, vcc, 0, v3, vcc
	flat_load_dword v37, v[2:3]
	s_cmp_gt_i32 s4, 3
	s_cselect_b64 s[4:5], -1, 0
	s_and_b64 vcc, exec, s[4:5]
	s_cbranch_vccnz .LBB0_157
	s_setprio 2
